# mixer-A job: the four gate loads of the gated store issued at job start together with the Q loads (same row address register)
# baseline (speedup 1.0000x reference)
.LBB0_477:
	s_and_b64 vcc, exec, s[8:9]
	s_cbranch_vccz .LBB0_495
	v_readlane_b32 s30, v254, 50
	v_ashrrev_i32_e32 v4, 1, v198
	s_lshl_b32 s26, s30, 7
	v_and_b32_e32 v0, 0xffffffe0, v4
	s_lshl_b32 s0, s10, 9
	v_and_b32_e32 v5, 31, v198
	v_add_u32_e32 v0, s26, v0
	s_and_b32 s0, s0, 0x7ffff800
	v_or_b32_e32 v0, v0, v5
	s_add_i32 s16, s0, 0xffff8000
	s_mov_b64 s[14:15], 0x3e38aa3b
	v_readlane_b32 s0, v254, 3
	s_mov_b32 s17, s15
	v_ashrrev_i32_e32 v1, 31, v0
	v_readlane_b32 s1, v254, 4
	s_waitcnt vmcnt(0)
	v_lshl_add_u64 v[98:99], v[0:1], 0, s[16:17]
	s_movk_i32 s17, 0x1d00
	v_mov_b64_e32 v[0:1], s[0:1]
	v_mad_u64_u32 v[0:1], s[0:1], v98, s17, v[0:1]
	s_lshl_b32 s0, s10, 6
	s_and_b32 s0, s0, 0xc0
	v_bfe_u32 v6, v198, 5, 1
	v_mad_i32_i24 v1, v99, s17, v1
	s_lshl_b32 s14, s0, 1
	v_lshl_add_u64 v[0:1], v[0:1], 0, s[14:15]
	v_lshlrev_b32_e32 v192, 4, v6
	v_lshl_add_u64 v[96:97], v[0:1], 0, v[192:193]
	global_load_dwordx4 v[64:67], v[96:97], off
	global_load_dwordx4 v[68:71], v[96:97], off offset:32
	global_load_dwordx4 v[72:75], v[96:97], off offset:64
	global_load_dwordx4 v[76:79], v[96:97], off offset:96
	global_load_dwordx4 v[200:203], v[96:97], off offset:1536
	global_load_dwordx4 v[204:207], v[96:97], off offset:1568
	global_load_dwordx4 v[208:211], v[96:97], off offset:1600
	global_load_dwordx4 v[212:215], v[96:97], off offset:1632
	s_movk_i32 s0, 0x880
	v_cmp_gt_i32_e32 vcc, s0, v198
	s_waitcnt lgkmcnt(0)
	s_barrier
	s_and_saveexec_b64 s[18:19], vcc
	s_movk_i32 s15, 0x90
	s_movk_i32 s27, 0x7f
	s_movk_i32 s28, 0x101
	s_movk_i32 s29, 0x281
	s_cbranch_execz .LBB0_486
	v_and_b32_e32 v1, 3, v198
	v_and_b32_e32 v0, 15, v198
	v_cmp_eq_u32_e32 vcc, 0, v1
	v_max_i32_e32 v1, 0x780, v198
	v_cmp_eq_u32_e64 s[0:1], 0, v0
	v_sub_u32_e32 v1, v1, v198
	v_add_u32_e32 v2, 0xff, v1
	v_cndmask_b32_e64 v0, 0, 1, s[0:1]
	s_movk_i32 s0, 0xff
	v_cmp_lt_u32_e64 s[0:1], s0, v2
	s_mov_b64 s[8:9], -1
	v_mov_b32_e32 v1, v198
	s_and_saveexec_b64 s[22:23], s[0:1]
	s_cbranch_execz .LBB0_483
	v_lshrrev_b32_e32 v1, 8, v2
	v_add_u32_e32 v7, 1, v1
	v_and_b32_e32 v8, 0x1fffffe, v7
	v_add_u32_e32 v199, 0x100, v198
	v_mov_b32_e32 v2, 0xe800
	v_mov_b32_e32 v1, v0
	v_lshl_add_u32 v9, v198, 2, v2
	s_mov_b64 s[24:25], 0
	v_mov_b32_e32 v10, v8
	v_mov_b64_e32 v[2:3], v[198:199]

.LBB0_714:
	v_cmp_lt_i32_e32 vcc, v109, v111
	v_lshlrev_b32_e32 v192, 1, v108
	v_readlane_b32 s76, v254, 37
	v_cndmask_b32_e32 v32, v110, v109, vcc
	v_lshlrev_b32_e32 v32, 2, v32
	ds_bpermute_b32 v32, v32, v34
	v_readlane_b32 s77, v254, 38
	s_waitcnt lgkmcnt(0)
	v_add_f32_e32 v32, v34, v32
	v_div_scale_f32 v33, s[0:1], v32, v32, 1.0
	v_rcp_f32_e32 v34, v33
	v_readlane_b32 s0, v254, 9
	v_readlane_b32 s1, v254, 10
	v_fma_f32 v35, -v33, v34, 1.0
	v_fmac_f32_e32 v34, v35, v34
	v_div_scale_f32 v35, vcc, 1.0, v32, 1.0
	v_mul_f32_e32 v36, v35, v34
	v_fma_f32 v37, -v33, v36, v35
	v_fmac_f32_e32 v36, v37, v34
	v_fma_f32 v33, -v33, v36, v35
	v_div_fmas_f32 v33, v33, v34, v36
	v_div_fixup_f32 v34, v33, v32, 1.0
	v_lshlrev_b64 v[32:33], 11, v[98:99]
	v_lshl_add_u64 v[32:33], s[0:1], 0, v[32:33]
	s_mov_b64 s[0:1], 0x3e38aa3b
	s_mov_b32 s15, s1
	v_lshl_add_u64 v[32:33], v[32:33], 0, s[14:15]
	v_lshl_add_u64 v[32:33], v[32:33], 0, v[192:193]
	s_waitcnt vmcnt(0)
	v_mov_b32_e32 v35, v202
	s_nop 1
	v_mov_b32_e32 v36, v200
	s_nop 1
	v_permlane32_swap_b32_e32 v36, v35
	v_lshlrev_b32_e32 v41, 16, v36
	v_and_b32_e32 v36, 0xffff0000, v36
	v_mov_b32_e32 v40, v203
	v_mul_f32_e32 v38, 0xbfb8aa3b, v41
	v_mul_f32_e32 v39, 0xbfb8aa3b, v36
	v_exp_f32_e32 v38, v38
	v_exp_f32_e32 v39, v39
	v_mov_b32_e32 v37, v201
	s_nop 1
	v_permlane32_swap_b32_e32 v37, v40
	v_pk_mul_f32 v[16:17], v[16:17], v[34:35] op_sel_hi:[1,0]
	v_pk_add_f32 v[38:39], v[38:39], 1.0 op_sel_hi:[1,0]
	v_pk_mul_f32 v[18:19], v[18:19], v[34:35] op_sel_hi:[1,0]
	v_div_scale_f32 v42, s[0:1], v39, v39, v36
	v_rcp_f32_e32 v43, v42
	s_nop 0
	v_fma_f32 v44, -v42, v43, 1.0
	v_fmac_f32_e32 v43, v44, v43
	v_div_scale_f32 v44, vcc, v36, v39, v36
	v_mul_f32_e32 v45, v44, v43
	v_fma_f32 v46, -v42, v45, v44
	v_fmac_f32_e32 v45, v46, v43
	v_fma_f32 v42, -v42, v45, v44
	v_div_fmas_f32 v42, v42, v43, v45
	v_div_fixup_f32 v39, v42, v39, v36
	v_div_scale_f32 v36, s[0:1], v38, v38, v41
	v_rcp_f32_e32 v42, v36
	s_nop 0
	v_fma_f32 v43, -v36, v42, 1.0
	v_fmac_f32_e32 v42, v43, v42
	v_div_scale_f32 v43, vcc, v41, v38, v41
	v_mul_f32_e32 v44, v43, v42
	v_fma_f32 v45, -v36, v44, v43
	v_fmac_f32_e32 v44, v45, v42
	v_fma_f32 v36, -v36, v44, v43
	v_div_fmas_f32 v36, v36, v42, v44
	v_div_fixup_f32 v38, v36, v38, v41
	v_pk_mul_f32 v[16:17], v[16:17], v[38:39]
	v_lshlrev_b32_e32 v38, 16, v37
	v_and_b32_e32 v39, 0xffff0000, v37
	v_mul_f32_e32 v36, 0xbfb8aa3b, v38
	v_mul_f32_e32 v37, 0xbfb8aa3b, v39
	v_exp_f32_e32 v36, v36
	v_exp_f32_e32 v37, v37
	v_cvt_pk_bf16_f32 v16, v16, v17
	v_pk_add_f32 v[36:37], v[36:37], 1.0 op_sel_hi:[1,0]
	s_nop 0
	v_div_scale_f32 v41, s[0:1], v37, v37, v39
	v_rcp_f32_e32 v42, v41
	s_nop 0
	v_fma_f32 v43, -v41, v42, 1.0
	v_fmac_f32_e32 v42, v43, v42
	v_div_scale_f32 v43, vcc, v39, v37, v39
	v_mul_f32_e32 v44, v43, v42
	v_fma_f32 v45, -v41, v44, v43
	v_fmac_f32_e32 v44, v45, v42
	v_fma_f32 v41, -v41, v44, v43
	v_div_fmas_f32 v41, v41, v42, v44
	v_div_fixup_f32 v37, v41, v37, v39
	v_div_scale_f32 v39, s[0:1], v36, v36, v38
	v_rcp_f32_e32 v41, v39
	s_nop 0
	v_fma_f32 v42, -v39, v41, 1.0
	v_fmac_f32_e32 v41, v42, v41
	v_div_scale_f32 v42, vcc, v38, v36, v38
	v_mul_f32_e32 v43, v42, v41
	v_fma_f32 v44, -v39, v43, v42
	v_fmac_f32_e32 v43, v44, v41
	v_fma_f32 v39, -v39, v43, v42
	v_div_fmas_f32 v39, v39, v41, v43
	v_div_fixup_f32 v36, v39, v36, v38
	v_lshlrev_b32_e32 v38, 16, v35
	v_and_b32_e32 v35, 0xffff0000, v35
	v_pk_mul_f32 v[18:19], v[18:19], v[36:37]
	v_mul_f32_e32 v36, 0xbfb8aa3b, v38
	v_mul_f32_e32 v37, 0xbfb8aa3b, v35
	v_exp_f32_e32 v36, v36
	v_exp_f32_e32 v37, v37
	v_pk_mul_f32 v[20:21], v[20:21], v[34:35] op_sel_hi:[1,0]
	v_cvt_pk_bf16_f32 v17, v18, v19
	v_pk_add_f32 v[36:37], v[36:37], 1.0 op_sel_hi:[1,0]
	s_nop 0
	v_div_scale_f32 v39, s[0:1], v37, v37, v35
	v_rcp_f32_e32 v41, v39
	s_nop 0
	v_fma_f32 v42, -v39, v41, 1.0
	v_fmac_f32_e32 v41, v42, v41
	v_div_scale_f32 v42, vcc, v35, v37, v35
	v_mul_f32_e32 v43, v42, v41
	v_fma_f32 v44, -v39, v43, v42
	v_fmac_f32_e32 v43, v44, v41
	v_fma_f32 v39, -v39, v43, v42
	v_div_fmas_f32 v39, v39, v41, v43
	v_div_fixup_f32 v37, v39, v37, v35
	v_div_scale_f32 v35, s[0:1], v36, v36, v38
	v_rcp_f32_e32 v39, v35
	s_nop 0
	v_fma_f32 v41, -v35, v39, 1.0
	v_fmac_f32_e32 v39, v41, v39
	v_div_scale_f32 v41, vcc, v38, v36, v38
	v_mul_f32_e32 v42, v41, v39
	v_fma_f32 v43, -v35, v42, v41
	v_fmac_f32_e32 v42, v43, v39
	v_fma_f32 v35, -v35, v42, v41
	v_div_fmas_f32 v35, v35, v39, v42
	v_div_fixup_f32 v36, v35, v36, v38
	v_lshlrev_b32_e32 v35, 16, v40
	v_and_b32_e32 v38, 0xffff0000, v40
	v_pk_mul_f32 v[20:21], v[20:21], v[36:37]
	v_mul_f32_e32 v36, 0xbfb8aa3b, v35
	v_mul_f32_e32 v37, 0xbfb8aa3b, v38
	v_exp_f32_e32 v36, v36
	v_exp_f32_e32 v37, v37
	v_pk_mul_f32 v[22:23], v[22:23], v[34:35] op_sel_hi:[1,0]
	v_cvt_pk_bf16_f32 v18, v20, v21
	s_nop 1
	v_permlane32_swap_b32_e32 v16, v18
	v_pk_add_f32 v[36:37], v[36:37], 1.0 op_sel_hi:[1,0]
	s_nop 0
	v_div_scale_f32 v39, s[0:1], v37, v37, v38
	v_rcp_f32_e32 v40, v39
	s_nop 0
	v_fma_f32 v41, -v39, v40, 1.0
	v_fmac_f32_e32 v40, v41, v40
	v_div_scale_f32 v41, vcc, v38, v37, v38
	v_mul_f32_e32 v42, v41, v40
	v_fma_f32 v43, -v39, v42, v41
	v_fmac_f32_e32 v42, v43, v40
	v_fma_f32 v39, -v39, v42, v41
	v_div_fmas_f32 v39, v39, v40, v42
	v_div_fixup_f32 v37, v39, v37, v38
	v_div_scale_f32 v38, s[0:1], v36, v36, v35
	v_rcp_f32_e32 v39, v38
	s_nop 0
	v_fma_f32 v40, -v38, v39, 1.0
	v_fmac_f32_e32 v39, v40, v39
	v_div_scale_f32 v40, vcc, v35, v36, v35
	v_mul_f32_e32 v41, v40, v39
	v_fma_f32 v42, -v38, v41, v40
	v_fmac_f32_e32 v41, v42, v39
	v_fma_f32 v38, -v38, v41, v40
	v_div_fmas_f32 v38, v38, v39, v41
	v_div_fixup_f32 v36, v38, v36, v35
	v_pk_mul_f32 v[22:23], v[22:23], v[36:37]
	s_nop 0
	v_cvt_pk_bf16_f32 v19, v22, v23
	s_nop 1
	v_permlane32_swap_b32_e32 v17, v19
	global_store_dwordx4 v[32:33], v[16:19], off
	s_waitcnt vmcnt(3)
	v_mov_b32_e32 v22, v206
	s_nop 1
	v_mov_b32_e32 v16, v204
	s_nop 1
	v_permlane32_swap_b32_e32 v16, v22
	v_lshlrev_b32_e32 v23, 16, v16
	v_and_b32_e32 v16, 0xffff0000, v16
	v_mul_f32_e32 v20, 0xbfb8aa3b, v23
	v_mul_f32_e32 v21, 0xbfb8aa3b, v16
	v_exp_f32_e32 v20, v20
	v_exp_f32_e32 v21, v21
	v_mov_b32_e32 v35, v207
	s_nop 1
	v_mov_b32_e32 v17, v205
	s_nop 1
	v_permlane32_swap_b32_e32 v17, v35
	v_pk_add_f32 v[20:21], v[20:21], 1.0 op_sel_hi:[1,0]
	v_pk_mul_f32 v[18:19], v[24:25], v[34:35] op_sel_hi:[1,0]
	v_div_scale_f32 v24, s[0:1], v21, v21, v16
	v_rcp_f32_e32 v25, v24
	s_nop 0
	v_fma_f32 v36, -v24, v25, 1.0
	v_fmac_f32_e32 v25, v36, v25
	v_div_scale_f32 v36, vcc, v16, v21, v16
	v_mul_f32_e32 v37, v36, v25
	v_fma_f32 v38, -v24, v37, v36
	v_fmac_f32_e32 v37, v38, v25
	v_fma_f32 v24, -v24, v37, v36
	v_div_fmas_f32 v24, v24, v25, v37
	v_div_fixup_f32 v21, v24, v21, v16
	v_div_scale_f32 v16, s[0:1], v20, v20, v23
	v_rcp_f32_e32 v24, v16
	s_nop 0
	v_fma_f32 v25, -v16, v24, 1.0
	v_fmac_f32_e32 v24, v25, v24
	v_div_scale_f32 v25, vcc, v23, v20, v23
	v_mul_f32_e32 v36, v25, v24
	v_fma_f32 v37, -v16, v36, v25
	v_fmac_f32_e32 v36, v37, v24
	v_fma_f32 v16, -v16, v36, v25
	v_div_fmas_f32 v16, v16, v24, v36
	v_div_fixup_f32 v20, v16, v20, v23
	v_lshlrev_b32_e32 v23, 16, v17
	v_and_b32_e32 v24, 0xffff0000, v17
	v_pk_mul_f32 v[18:19], v[18:19], v[20:21]
	v_mul_f32_e32 v20, 0xbfb8aa3b, v23
	v_mul_f32_e32 v21, 0xbfb8aa3b, v24
	v_exp_f32_e32 v20, v20
	v_exp_f32_e32 v21, v21
	v_pk_mul_f32 v[16:17], v[26:27], v[34:35] op_sel_hi:[1,0]
	v_pk_add_f32 v[20:21], v[20:21], 1.0 op_sel_hi:[1,0]
	s_nop 0
	v_div_scale_f32 v25, s[0:1], v21, v21, v24
	v_rcp_f32_e32 v26, v25
	s_nop 0
	v_fma_f32 v27, -v25, v26, 1.0
	v_fmac_f32_e32 v26, v27, v26
	v_div_scale_f32 v27, vcc, v24, v21, v24
	v_mul_f32_e32 v36, v27, v26
	v_fma_f32 v37, -v25, v36, v27
	v_fmac_f32_e32 v36, v37, v26
	v_fma_f32 v25, -v25, v36, v27
	v_div_fmas_f32 v25, v25, v26, v36
	v_div_fixup_f32 v21, v25, v21, v24
	v_div_scale_f32 v24, s[0:1], v20, v20, v23
	v_rcp_f32_e32 v25, v24
	s_nop 0
	v_fma_f32 v26, -v24, v25, 1.0
	v_fmac_f32_e32 v25, v26, v25
	v_div_scale_f32 v26, vcc, v23, v20, v23
	v_mul_f32_e32 v27, v26, v25
	v_fma_f32 v36, -v24, v27, v26
	v_fmac_f32_e32 v27, v36, v25
	v_fma_f32 v24, -v24, v27, v26
	v_div_fmas_f32 v24, v24, v25, v27
	v_div_fixup_f32 v20, v24, v20, v23
	v_lshlrev_b32_e32 v24, 16, v22
	v_and_b32_e32 v25, 0xffff0000, v22
	v_mul_f32_e32 v22, 0xbfb8aa3b, v24
	v_mul_f32_e32 v23, 0xbfb8aa3b, v25
	v_exp_f32_e32 v22, v22
	v_exp_f32_e32 v23, v23
	v_pk_mul_f32 v[20:21], v[16:17], v[20:21]
	v_pk_mul_f32 v[16:17], v[28:29], v[34:35] op_sel_hi:[1,0]
	v_pk_add_f32 v[22:23], v[22:23], 1.0 op_sel_hi:[1,0]
	s_nop 0
	v_div_scale_f32 v26, s[0:1], v23, v23, v25
	v_rcp_f32_e32 v27, v26
	s_nop 0
	v_fma_f32 v28, -v26, v27, 1.0
	v_fmac_f32_e32 v27, v28, v27
	v_div_scale_f32 v28, vcc, v25, v23, v25
	v_mul_f32_e32 v29, v28, v27
	v_fma_f32 v36, -v26, v29, v28
	v_fmac_f32_e32 v29, v36, v27
	v_fma_f32 v26, -v26, v29, v28
	v_div_fmas_f32 v26, v26, v27, v29
	v_div_fixup_f32 v23, v26, v23, v25
	v_div_scale_f32 v25, s[0:1], v22, v22, v24
	v_rcp_f32_e32 v26, v25
	s_nop 0
	v_fma_f32 v27, -v25, v26, 1.0
	v_fmac_f32_e32 v26, v27, v26
	v_div_scale_f32 v27, vcc, v24, v22, v24
	v_mul_f32_e32 v28, v27, v26
	v_fma_f32 v29, -v25, v28, v27
	v_fmac_f32_e32 v28, v29, v26
	v_fma_f32 v25, -v25, v28, v27
	v_div_fmas_f32 v25, v25, v26, v28
	v_lshlrev_b32_e32 v26, 16, v35
	v_and_b32_e32 v27, 0xffff0000, v35
	v_div_fixup_f32 v22, v25, v22, v24
	v_mul_f32_e32 v24, 0xbfb8aa3b, v26
	v_mul_f32_e32 v25, 0xbfb8aa3b, v27
	v_exp_f32_e32 v24, v24
	v_exp_f32_e32 v25, v25
	v_pk_mul_f32 v[22:23], v[16:17], v[22:23]
	v_pk_mul_f32 v[16:17], v[30:31], v[34:35] op_sel_hi:[1,0]
	v_pk_add_f32 v[24:25], v[24:25], 1.0 op_sel_hi:[1,0]
	s_nop 0
	v_div_scale_f32 v28, s[0:1], v25, v25, v27
	v_rcp_f32_e32 v29, v28
	s_nop 0
	v_fma_f32 v30, -v28, v29, 1.0
	v_fmac_f32_e32 v29, v30, v29
	v_div_scale_f32 v30, vcc, v27, v25, v27
	v_mul_f32_e32 v31, v30, v29
	v_fma_f32 v35, -v28, v31, v30
	v_fmac_f32_e32 v31, v35, v29
	v_fma_f32 v28, -v28, v31, v30
	v_div_fmas_f32 v28, v28, v29, v31
	v_div_fixup_f32 v25, v28, v25, v27
	v_div_scale_f32 v27, s[0:1], v24, v24, v26
	v_rcp_f32_e32 v28, v27
	v_pk_mul_f32 v[0:1], v[0:1], v[34:35] op_sel_hi:[1,0]
	v_pk_mul_f32 v[2:3], v[2:3], v[34:35] op_sel_hi:[1,0]
	v_pk_mul_f32 v[4:5], v[4:5], v[34:35] op_sel_hi:[1,0]
	v_fma_f32 v29, -v27, v28, 1.0
	v_fmac_f32_e32 v28, v29, v28
	v_div_scale_f32 v29, vcc, v26, v24, v26
	v_mul_f32_e32 v30, v29, v28
	v_fma_f32 v31, -v27, v30, v29
	v_fmac_f32_e32 v30, v31, v28
	v_fma_f32 v27, -v27, v30, v29
	v_div_fmas_f32 v27, v27, v28, v30
	v_div_fixup_f32 v24, v27, v24, v26
	v_pk_mul_f32 v[24:25], v[16:17], v[24:25]
	v_cvt_pk_bf16_f32 v16, v18, v19
	v_cvt_pk_bf16_f32 v17, v20, v21
	v_cvt_pk_bf16_f32 v18, v22, v23
	v_cvt_pk_bf16_f32 v19, v24, v25
	s_nop 0
	v_permlane32_swap_b32_e32 v16, v18
	v_permlane32_swap_b32_e32 v17, v19
	global_store_dwordx4 v[32:33], v[16:19], off offset:32
	v_pk_mul_f32 v[6:7], v[6:7], v[34:35] op_sel_hi:[1,0]
	s_waitcnt vmcnt(3)
	v_mov_b32_e32 v20, v210
	s_nop 1
	v_mov_b32_e32 v16, v208
	s_nop 1
	v_permlane32_swap_b32_e32 v16, v20
	v_lshlrev_b32_e32 v22, 16, v16
	v_and_b32_e32 v16, 0xffff0000, v16
	v_mov_b32_e32 v21, v211
	v_mul_f32_e32 v18, 0xbfb8aa3b, v22
	v_mul_f32_e32 v19, 0xbfb8aa3b, v16
	v_exp_f32_e32 v18, v18
	v_exp_f32_e32 v19, v19
	v_mov_b32_e32 v17, v209
	s_nop 1
	v_permlane32_swap_b32_e32 v17, v21
	v_pk_add_f32 v[18:19], v[18:19], 1.0 op_sel_hi:[1,0]
	s_nop 0
	v_div_scale_f32 v23, s[0:1], v19, v19, v16
	v_rcp_f32_e32 v24, v23
	s_nop 0
	v_fma_f32 v25, -v23, v24, 1.0
	v_fmac_f32_e32 v24, v25, v24
	v_div_scale_f32 v25, vcc, v16, v19, v16
	v_mul_f32_e32 v26, v25, v24
	v_fma_f32 v27, -v23, v26, v25
	v_fmac_f32_e32 v26, v27, v24
	v_fma_f32 v23, -v23, v26, v25
	v_div_fmas_f32 v23, v23, v24, v26
	v_div_fixup_f32 v19, v23, v19, v16
	v_div_scale_f32 v16, s[0:1], v18, v18, v22
	v_rcp_f32_e32 v23, v16
	s_nop 0
	v_fma_f32 v24, -v16, v23, 1.0
	v_fmac_f32_e32 v23, v24, v23
	v_div_scale_f32 v24, vcc, v22, v18, v22
	v_mul_f32_e32 v25, v24, v23
	v_fma_f32 v26, -v16, v25, v24
	v_fmac_f32_e32 v25, v26, v23
	v_fma_f32 v16, -v16, v25, v24
	v_div_fmas_f32 v16, v16, v23, v25
	v_div_fixup_f32 v18, v16, v18, v22
	v_pk_mul_f32 v[0:1], v[0:1], v[18:19]
	v_lshlrev_b32_e32 v18, 16, v17
	v_and_b32_e32 v19, 0xffff0000, v17
	v_mul_f32_e32 v16, 0xbfb8aa3b, v18
	v_mul_f32_e32 v17, 0xbfb8aa3b, v19
	v_exp_f32_e32 v16, v16
	v_exp_f32_e32 v17, v17
	v_cvt_pk_bf16_f32 v0, v0, v1
	v_pk_add_f32 v[16:17], v[16:17], 1.0 op_sel_hi:[1,0]
	s_nop 0
	v_div_scale_f32 v22, s[0:1], v17, v17, v19
	v_rcp_f32_e32 v23, v22
	s_nop 0
	v_fma_f32 v24, -v22, v23, 1.0
	v_fmac_f32_e32 v23, v24, v23
	v_div_scale_f32 v24, vcc, v19, v17, v19
	v_mul_f32_e32 v25, v24, v23
	v_fma_f32 v26, -v22, v25, v24
	v_fmac_f32_e32 v25, v26, v23
	v_fma_f32 v22, -v22, v25, v24
	v_div_fmas_f32 v22, v22, v23, v25
	v_div_fixup_f32 v17, v22, v17, v19
	v_div_scale_f32 v19, s[0:1], v16, v16, v18
	v_rcp_f32_e32 v22, v19
	s_nop 0
	v_fma_f32 v23, -v19, v22, 1.0
	v_fmac_f32_e32 v22, v23, v22
	v_div_scale_f32 v23, vcc, v18, v16, v18
	v_mul_f32_e32 v24, v23, v22
	v_fma_f32 v25, -v19, v24, v23
	v_fmac_f32_e32 v24, v25, v22
	v_fma_f32 v19, -v19, v24, v23
	v_div_fmas_f32 v19, v19, v22, v24
	v_div_fixup_f32 v16, v19, v16, v18
	v_lshlrev_b32_e32 v18, 16, v20
	v_and_b32_e32 v19, 0xffff0000, v20
	v_pk_mul_f32 v[2:3], v[2:3], v[16:17]
	v_mul_f32_e32 v16, 0xbfb8aa3b, v18
	v_mul_f32_e32 v17, 0xbfb8aa3b, v19
	v_exp_f32_e32 v16, v16
	v_exp_f32_e32 v17, v17
	v_cvt_pk_bf16_f32 v1, v2, v3
	v_pk_add_f32 v[16:17], v[16:17], 1.0 op_sel_hi:[1,0]
	s_nop 0
	v_div_scale_f32 v20, s[0:1], v17, v17, v19
	v_rcp_f32_e32 v22, v20
	s_nop 0
	v_fma_f32 v23, -v20, v22, 1.0
	v_fmac_f32_e32 v22, v23, v22
	v_div_scale_f32 v23, vcc, v19, v17, v19
	v_mul_f32_e32 v24, v23, v22
	v_fma_f32 v25, -v20, v24, v23
	v_fmac_f32_e32 v24, v25, v22
	v_fma_f32 v20, -v20, v24, v23
	v_div_fmas_f32 v20, v20, v22, v24
	v_div_fixup_f32 v17, v20, v17, v19
	v_div_scale_f32 v19, s[0:1], v16, v16, v18
	v_rcp_f32_e32 v20, v19
	s_nop 0
	v_fma_f32 v22, -v19, v20, 1.0
	v_fmac_f32_e32 v20, v22, v20
	v_div_scale_f32 v22, vcc, v18, v16, v18
	v_mul_f32_e32 v23, v22, v20
	v_fma_f32 v24, -v19, v23, v22
	v_fmac_f32_e32 v23, v24, v20
	v_fma_f32 v19, -v19, v23, v22
	v_div_fmas_f32 v19, v19, v20, v23
	v_div_fixup_f32 v16, v19, v16, v18
	v_lshlrev_b32_e32 v18, 16, v21
	v_and_b32_e32 v19, 0xffff0000, v21
	v_pk_mul_f32 v[4:5], v[4:5], v[16:17]
	v_mul_f32_e32 v16, 0xbfb8aa3b, v18
	v_mul_f32_e32 v17, 0xbfb8aa3b, v19
	v_exp_f32_e32 v16, v16
	v_exp_f32_e32 v17, v17
	v_cvt_pk_bf16_f32 v2, v4, v5
	s_nop 1
	v_permlane32_swap_b32_e32 v0, v2
	v_pk_add_f32 v[16:17], v[16:17], 1.0 op_sel_hi:[1,0]
	s_nop 0
	v_div_scale_f32 v20, s[0:1], v17, v17, v19
	v_rcp_f32_e32 v21, v20
	s_nop 0
	v_fma_f32 v22, -v20, v21, 1.0
	v_fmac_f32_e32 v21, v22, v21
	v_div_scale_f32 v22, vcc, v19, v17, v19
	v_mul_f32_e32 v23, v22, v21
	v_fma_f32 v24, -v20, v23, v22
	v_fmac_f32_e32 v23, v24, v21
	v_fma_f32 v20, -v20, v23, v22
	v_div_fmas_f32 v20, v20, v21, v23
	v_div_fixup_f32 v17, v20, v17, v19
	v_div_scale_f32 v19, s[0:1], v16, v16, v18
	v_rcp_f32_e32 v20, v19
	s_nop 0
	v_fma_f32 v21, -v19, v20, 1.0
	v_fmac_f32_e32 v20, v21, v20
	v_div_scale_f32 v21, vcc, v18, v16, v18
	v_mul_f32_e32 v22, v21, v20
	v_fma_f32 v23, -v19, v22, v21
	v_fmac_f32_e32 v22, v23, v20
	v_fma_f32 v19, -v19, v22, v21
	v_div_fmas_f32 v19, v19, v20, v22
	v_div_fixup_f32 v16, v19, v16, v18
	v_pk_mul_f32 v[6:7], v[6:7], v[16:17]
	s_nop 0
	v_cvt_pk_bf16_f32 v3, v6, v7
	s_nop 1
	v_permlane32_swap_b32_e32 v1, v3
	global_store_dwordx4 v[32:33], v[0:3], off offset:64
	s_waitcnt vmcnt(3)
	v_mov_b32_e32 v6, v214
	s_nop 1
	v_mov_b32_e32 v0, v212
	s_nop 1
	v_permlane32_swap_b32_e32 v0, v6
	v_lshlrev_b32_e32 v7, 16, v0
	v_and_b32_e32 v0, 0xffff0000, v0
	v_mul_f32_e32 v4, 0xbfb8aa3b, v7
	v_mul_f32_e32 v5, 0xbfb8aa3b, v0
	v_exp_f32_e32 v4, v4
	v_exp_f32_e32 v5, v5
	v_mov_b32_e32 v16, v215
	v_pk_mul_f32 v[2:3], v[8:9], v[34:35] op_sel_hi:[1,0]
	s_nop 0
	v_mov_b32_e32 v1, v213
	s_nop 1
	v_permlane32_swap_b32_e32 v1, v16
	v_pk_add_f32 v[4:5], v[4:5], 1.0 op_sel_hi:[1,0]
	s_nop 0
	v_div_scale_f32 v8, s[0:1], v5, v5, v0
	v_rcp_f32_e32 v9, v8
	s_nop 0
	v_fma_f32 v17, -v8, v9, 1.0
	v_fmac_f32_e32 v9, v17, v9
	v_div_scale_f32 v17, vcc, v0, v5, v0
	v_mul_f32_e32 v18, v17, v9
	v_fma_f32 v19, -v8, v18, v17
	v_fmac_f32_e32 v18, v19, v9
	v_fma_f32 v8, -v8, v18, v17
	v_div_fmas_f32 v8, v8, v9, v18
	v_div_fixup_f32 v5, v8, v5, v0
	v_div_scale_f32 v0, s[0:1], v4, v4, v7
	v_rcp_f32_e32 v8, v0
	s_nop 0
	v_fma_f32 v9, -v0, v8, 1.0
	v_fmac_f32_e32 v8, v9, v8
	v_div_scale_f32 v9, vcc, v7, v4, v7
	v_mul_f32_e32 v17, v9, v8
	v_fma_f32 v18, -v0, v17, v9
	v_fmac_f32_e32 v17, v18, v8
	v_fma_f32 v0, -v0, v17, v9
	v_div_fmas_f32 v0, v0, v8, v17
	v_div_fixup_f32 v4, v0, v4, v7
	v_lshlrev_b32_e32 v7, 16, v1
	v_and_b32_e32 v8, 0xffff0000, v1
	v_pk_mul_f32 v[2:3], v[2:3], v[4:5]
	v_mul_f32_e32 v4, 0xbfb8aa3b, v7
	v_mul_f32_e32 v5, 0xbfb8aa3b, v8
	v_exp_f32_e32 v4, v4
	v_exp_f32_e32 v5, v5
	v_pk_mul_f32 v[0:1], v[10:11], v[34:35] op_sel_hi:[1,0]
	v_pk_add_f32 v[4:5], v[4:5], 1.0 op_sel_hi:[1,0]
	s_nop 0
	v_div_scale_f32 v9, s[0:1], v5, v5, v8
	v_rcp_f32_e32 v10, v9
	s_nop 0
	v_fma_f32 v11, -v9, v10, 1.0
	v_fmac_f32_e32 v10, v11, v10
	v_div_scale_f32 v11, vcc, v8, v5, v8
	v_mul_f32_e32 v17, v11, v10
	v_fma_f32 v18, -v9, v17, v11
	v_fmac_f32_e32 v17, v18, v10
	v_fma_f32 v9, -v9, v17, v11
	v_div_fmas_f32 v9, v9, v10, v17
	v_div_fixup_f32 v5, v9, v5, v8
	v_div_scale_f32 v8, s[0:1], v4, v4, v7
	v_rcp_f32_e32 v9, v8
	s_nop 0
	v_fma_f32 v10, -v8, v9, 1.0
	v_fmac_f32_e32 v9, v10, v9
	v_div_scale_f32 v10, vcc, v7, v4, v7
	v_mul_f32_e32 v11, v10, v9
	v_fma_f32 v17, -v8, v11, v10
	v_fmac_f32_e32 v11, v17, v9
	v_fma_f32 v8, -v8, v11, v10
	v_div_fmas_f32 v8, v8, v9, v11
	v_div_fixup_f32 v4, v8, v4, v7
	v_lshlrev_b32_e32 v8, 16, v6
	v_and_b32_e32 v9, 0xffff0000, v6
	v_mul_f32_e32 v6, 0xbfb8aa3b, v8
	v_mul_f32_e32 v7, 0xbfb8aa3b, v9
	v_exp_f32_e32 v6, v6
	v_exp_f32_e32 v7, v7
	v_pk_mul_f32 v[4:5], v[0:1], v[4:5]
	v_pk_mul_f32 v[0:1], v[12:13], v[34:35] op_sel_hi:[1,0]
	v_pk_add_f32 v[6:7], v[6:7], 1.0 op_sel_hi:[1,0]
	s_nop 0
	v_div_scale_f32 v10, s[0:1], v7, v7, v9
	v_rcp_f32_e32 v11, v10
	s_nop 0
	v_fma_f32 v12, -v10, v11, 1.0
	v_fmac_f32_e32 v11, v12, v11
	v_div_scale_f32 v12, vcc, v9, v7, v9
	v_mul_f32_e32 v13, v12, v11
	v_fma_f32 v17, -v10, v13, v12
	v_fmac_f32_e32 v13, v17, v11
	v_fma_f32 v10, -v10, v13, v12
	v_div_fmas_f32 v10, v10, v11, v13
	v_div_fixup_f32 v7, v10, v7, v9
	v_div_scale_f32 v9, s[0:1], v6, v6, v8
	v_rcp_f32_e32 v10, v9
	s_nop 0
	v_fma_f32 v11, -v9, v10, 1.0
	v_fmac_f32_e32 v10, v11, v10
	v_div_scale_f32 v11, vcc, v8, v6, v8
	v_mul_f32_e32 v12, v11, v10
	v_fma_f32 v13, -v9, v12, v11
	v_fmac_f32_e32 v12, v13, v10
	v_fma_f32 v9, -v9, v12, v11
	v_div_fmas_f32 v9, v9, v10, v12
	v_lshlrev_b32_e32 v10, 16, v16
	v_and_b32_e32 v11, 0xffff0000, v16
	v_div_fixup_f32 v6, v9, v6, v8
	v_mul_f32_e32 v8, 0xbfb8aa3b, v10
	v_mul_f32_e32 v9, 0xbfb8aa3b, v11
	v_exp_f32_e32 v8, v8
	v_exp_f32_e32 v9, v9
	v_pk_mul_f32 v[6:7], v[0:1], v[6:7]
	v_pk_mul_f32 v[0:1], v[14:15], v[34:35] op_sel_hi:[1,0]
	v_pk_add_f32 v[8:9], v[8:9], 1.0 op_sel_hi:[1,0]
	s_nop 0
	v_div_scale_f32 v12, s[0:1], v9, v9, v11
	v_rcp_f32_e32 v13, v12
	s_nop 0
	v_fma_f32 v14, -v12, v13, 1.0
	v_fmac_f32_e32 v13, v14, v13
	v_div_scale_f32 v14, vcc, v11, v9, v11
	v_mul_f32_e32 v15, v14, v13
	v_fma_f32 v16, -v12, v15, v14
	v_fmac_f32_e32 v15, v16, v13
	v_fma_f32 v12, -v12, v15, v14
	v_div_fmas_f32 v12, v12, v13, v15
	v_div_fixup_f32 v9, v12, v9, v11
	v_div_scale_f32 v11, s[0:1], v8, v8, v10
	v_rcp_f32_e32 v12, v11
	s_nop 0
	v_fma_f32 v13, -v11, v12, 1.0
	v_fmac_f32_e32 v12, v13, v12
	v_div_scale_f32 v13, vcc, v10, v8, v10
	v_mul_f32_e32 v14, v13, v12
	v_fma_f32 v15, -v11, v14, v13
	v_fmac_f32_e32 v14, v15, v12
	v_fma_f32 v11, -v11, v14, v13
	v_div_fmas_f32 v11, v11, v12, v14
	v_div_fixup_f32 v8, v11, v8, v10
	v_pk_mul_f32 v[8:9], v[0:1], v[8:9]
	v_cvt_pk_bf16_f32 v0, v2, v3
	v_cvt_pk_bf16_f32 v1, v4, v5
	v_cvt_pk_bf16_f32 v2, v6, v7
	v_cvt_pk_bf16_f32 v3, v8, v9
	s_nop 0
	v_permlane32_swap_b32_e32 v0, v2
	v_permlane32_swap_b32_e32 v1, v3
	global_store_dwordx4 v[32:33], v[0:3], off offset:96
